# P1: accumulators re-zeroed inside the pipelined epilogue (per group, under the LDS exchange); the 127-v_mov run before each K-loop removed
# baseline (speedup 1.0000x reference)
;     __device__ __forceinline__ bool next(int i, Unit& u) const { if (i >= n) return false; u.pm = pm + i * dpm; u.pn = first + i * dpn; return true; }
; #define PG8_WAIT_V(n) asm volatile("s_waitcnt vmcnt(" #n ")" ::: "memory")
; template <class Epi, class Sched, bool ALIGN_EPI = false, bool SP2 = false>
; __device__ __forceinline__ void gemm_phase(PG8_LAS unsigned char* lds, const Gemm g, const Sched& S, const Epi& E) {
;     ...
;     for (int i = 0; i < 2; ++i) { int R, C; stage_rc(tid * 16 + i * 8192, R, C); const int Rb = Epi::PERM ? ((R & ~31) + perm32(R & 31)) : R;
;         voffA[i] = (unsigned)(R * K + C) * 2u; voffB[i] = (unsigned)(Rb * K + C) * 2u; }
;     const size_t kstep = (size_t)(BK * 2);
;     const size_t hstep = (size_t)HALF * K * 2;
;     const size_t tstep = 2 * hstep;
;     const unsigned ldsw = (unsigned)wid * 1024u;
;     const int aoff = lds_byte(wr * 64 + fr, fq * 8), boff = lds_byte(wc * 32 + fr, fq * 8);
;     ...
;     Unit cur, nxt; int ui = 0;
;     if (!S.next(0, cur)) return;
;     f32x4 acc[2][2][4][2];
; #pragma unroll
;     for (int a = 0; a < 2; ++a)
; #pragma unroll
;         for (int b = 0; b < 2; ++b)
; #pragma unroll
;             for (int m = 0; m < 4; ++m)
; #pragma unroll
;                 for (int n = 0; n < 2; ++n) acc[a][b][m][n] = (f32x4){0.f, 0.f, 0.f, 0.f};
;     bf16x8 At[4][2], B0[2][2], B1[2][2];
;     const char* cA = (const char*)g.A + (size_t)cur.pm * tstep; const char* cB = (const char*)g.Bt + (size_t)cur.pn * tstep;
;     S.a_ready(cur);
;     if constexpr (SP2) {
;         PG8_STAGE(PG8_SB(0, 0), cB, voffB); PG8_STAGE(PG8_SB(0, 1), cB + hstep, voffB); PG8_STAGE(PG8_SA(0, 0), cA, voffA); PG8_STAGE(PG8_SA(0, 1), cA + hstep, voffA);
;         if (wr == 1) PG8_BAR;
;         PG8_WAIT_V(2); PG8_BAR;
;         PG8_STAGE(PG8_SB(1, 0), cB + kstep, voffB); PG8_STAGE(PG8_SA(1, 0), cA + kstep, voffA); PG8_STAGE(PG8_SB(1, 1), cB + hstep + kstep, voffB);
;         PG8_WAIT_V(6); PG8_BAR;
;     } else {
;         PG8_STAGE(PG8_SB(0, 0), cB, voffB); PG8_STAGE(PG8_SA(0, 0), cA, voffA); PG8_STAGE(PG8_SB(0, 1), cB + hstep, voffB); PG8_STAGE(PG8_SA(0, 1), cA + hstep, voffA);
;         if (wr == 1) PG8_BAR;
;         PG8_WAIT_V(4); PG8_BAR;
;         PG8_STAGE(PG8_SB(1, 0), cB + kstep, voffB); PG8_STAGE(PG8_SA(1, 0), cA + kstep, voffA); PG8_STAGE(PG8_SB(1, 1), cB + hstep + kstep, voffB);
;         PG8_WAIT_V(6); PG8_BAR;
.LBB0_242:
	v_lshl_add_u64 v[10:11], s[58:59], 0, v[130:131]
	v_mov_b32_e32 v143, v131
	v_lshl_add_u64 v[12:13], s[58:59], 0, v[142:143]
	v_mov_b32_e32 v147, v131
	s_add_i32 m0, s11, 0x18000
	v_lshl_add_u64 v[10:11], v[10:11], 0, s[46:47]
	v_lshl_add_u64 v[14:15], s[62:63], 0, v[146:147]
	v_mov_b32_e32 v145, v131
	s_waitcnt vmcnt(2)
	s_barrier
	global_load_lds_dwordx4 v[10:11], off
	v_lshl_add_u64 v[10:11], v[12:13], 0, s[46:47]
	s_add_i32 m0, s11, 0x1a000
	s_add_i32 s38, s11, 0x8000
	v_lshl_add_u64 v[16:17], s[62:63], 0, v[144:145]
	global_load_lds_dwordx4 v[10:11], off
	v_lshl_add_u64 v[10:11], v[14:15], 0, s[46:47]
	s_mov_b32 m0, s38
	s_add_i32 s39, s11, 0xa000
	v_readlane_b32 s12, v247, 43
	global_load_lds_dwordx4 v[10:11], off
	v_lshl_add_u64 v[10:11], v[16:17], 0, s[46:47]
	s_mov_b32 m0, s39
	v_readlane_b32 s13, v247, 44
	global_load_lds_dwordx4 v[10:11], off
	s_add_i32 m0, s11, 0x1c000
	v_lshl_add_u64 v[10:11], s[12:13], 0, v[130:131]
	global_load_lds_dwordx4 v[10:11], off
	v_lshl_add_u64 v[10:11], s[12:13], 0, v[142:143]
	s_add_i32 m0, s11, 0x1e000
	v_lshlrev_b32_e32 v13, 2, v3
	global_load_lds_dwordx4 v[10:11], off
	v_and_b32_e32 v10, 15, v3
	v_and_b32_e32 v11, 48, v3
	s_and_b32 s1, s1, 3
	s_lshl_b32 s10, s2, 13
	v_lshl_or_b32 v12, v10, 6, v11
	v_and_b32_e32 v13, 32, v13
	v_bitop3_b32 v14, v12, s10, v13 bitop3:0xde
	s_lshl_b32 s10, s1, 12
	s_cmpk_lt_u32 s0, 0x100
	s_cselect_b64 s[48:49], -1, 0
	s_lshl_b32 s0, s2, 2
	s_or_b32 s0, s0, s1
	s_mulk_i32 s0, 0x900
	v_bitop3_b32 v133, v12, s10, v13 bitop3:0xde
	v_bfe_u32 v12, v3, 2, 4
	v_lshlrev_b32_e32 v3, 3, v3
	s_add_i32 s0, s0, 0
	v_and_b32_e32 v3, 24, v3
	s_add_i32 s0, s0, 0x20200
	v_lshl_or_b32 v156, s1, 5, v3
	v_mul_u32_u24_e32 v3, 0x50, v10
	v_add_u32_e32 v10, s0, v11
	v_mov_b32_e32 v11, s0
	s_movk_i32 s0, 0x50
	v_lshl_or_b32 v157, s2, 6, v12
	v_mad_u32_u24 v11, v12, s0, v11
	v_lshlrev_b32_e32 v12, 14, v8
	v_and_b32_e32 v12, 0xffff8000, v12
	v_lshl_add_u32 v7, v7, 11, v12
	v_and_b32_e32 v8, 1, v8
	v_lshl_or_b32 v7, v8, 6, v7
	v_lshl_add_u32 v148, v9, 1, v7
	v_lshlrev_b32_e32 v7, 14, v2
	v_and_b32_e32 v7, 0xffff8000, v7
	s_waitcnt vmcnt(6)
	v_lshl_add_u32 v4, v4, 11, v7
	v_and_b32_e32 v2, 1, v2
	v_and_b32_e32 v5, 48, v5
	v_lshl_or_b32 v2, v2, 6, v4
	v_readlane_b32 s0, v247, 37
	v_mov_b32_e32 v149, v131
	v_lshl_add_u32 v150, v6, 1, v2
	v_mov_b32_e32 v151, v131
	s_mov_b32 s42, 0
	v_add_u32_e32 v158, 0, v14
	v_add_u32_e32 v159, v10, v3
	v_add_u32_e32 v160, v11, v5
	s_mov_b32 s44, s19
	s_mov_b32 s43, s0
	s_mov_b64 s[20:21], s[58:59]
	s_mov_b64 s[22:23], s[62:63]
	s_mov_b64 s[56:57], s[62:63]
	s_barrier
	v_readlane_b32 s1, v247, 38
	v_mov_b32_e32 v3, 0
	v_mov_b32_e32 v4, 0
	v_mov_b32_e32 v5, 0
	v_mov_b32_e32 v6, 0
	v_mov_b32_e32 v7, 0
	v_mov_b32_e32 v8, 0
	v_mov_b32_e32 v9, 0
	v_mov_b32_e32 v10, 0
	v_mov_b32_e32 v11, 0
	v_mov_b32_e32 v12, 0
	v_mov_b32_e32 v13, 0
	v_mov_b32_e32 v14, 0
	v_mov_b32_e32 v15, 0
	v_mov_b32_e32 v16, 0
	v_mov_b32_e32 v17, 0
	v_mov_b32_e32 v18, 0
	v_mov_b32_e32 v19, 0
	v_mov_b32_e32 v20, 0
	v_mov_b32_e32 v21, 0
	v_mov_b32_e32 v22, 0
	v_mov_b32_e32 v23, 0
	v_mov_b32_e32 v24, 0
	v_mov_b32_e32 v25, 0
	v_mov_b32_e32 v26, 0
	v_mov_b32_e32 v27, 0
	v_mov_b32_e32 v28, 0
	v_mov_b32_e32 v29, 0
	v_mov_b32_e32 v30, 0
	v_mov_b32_e32 v31, 0
	v_mov_b32_e32 v32, 0
	v_mov_b32_e32 v33, 0
	v_mov_b32_e32 v34, 0
	v_mov_b32_e32 v35, 0
	v_mov_b32_e32 v36, 0
	v_mov_b32_e32 v37, 0
	v_mov_b32_e32 v38, 0
	v_mov_b32_e32 v39, 0
	v_mov_b32_e32 v40, 0
	v_mov_b32_e32 v41, 0
	v_mov_b32_e32 v42, 0
	v_mov_b32_e32 v43, 0
	v_mov_b32_e32 v44, 0
	v_mov_b32_e32 v45, 0
	v_mov_b32_e32 v46, 0
	v_mov_b32_e32 v47, 0
	v_mov_b32_e32 v48, 0
	v_mov_b32_e32 v49, 0
	v_mov_b32_e32 v50, 0
	v_mov_b32_e32 v51, 0
	v_mov_b32_e32 v52, 0
	v_mov_b32_e32 v53, 0
	v_mov_b32_e32 v54, 0
	v_mov_b32_e32 v55, 0
	v_mov_b32_e32 v56, 0
	v_mov_b32_e32 v57, 0
	v_mov_b32_e32 v58, 0
	v_mov_b32_e32 v59, 0
	v_mov_b32_e32 v60, 0
	v_mov_b32_e32 v61, 0
	v_mov_b32_e32 v62, 0
	v_mov_b32_e32 v63, 0
	v_mov_b32_e32 v64, 0
	v_mov_b32_e32 v65, 0
	v_mov_b32_e32 v66, 0
	v_mov_b32_e32 v67, 0
	v_mov_b32_e32 v68, 0
	v_mov_b32_e32 v69, 0
	v_mov_b32_e32 v70, 0
	v_mov_b32_e32 v71, 0
	v_mov_b32_e32 v72, 0
	v_mov_b32_e32 v73, 0
	v_mov_b32_e32 v74, 0
	v_mov_b32_e32 v75, 0
	v_mov_b32_e32 v76, 0
	v_mov_b32_e32 v77, 0
	v_mov_b32_e32 v78, 0
	v_mov_b32_e32 v79, 0
	v_mov_b32_e32 v80, 0
	v_mov_b32_e32 v81, 0
	v_mov_b32_e32 v82, 0
	v_mov_b32_e32 v83, 0
	v_mov_b32_e32 v84, 0
	v_mov_b32_e32 v85, 0
	v_mov_b32_e32 v86, 0
	v_mov_b32_e32 v87, 0
	v_mov_b32_e32 v88, 0
	v_mov_b32_e32 v89, 0
	v_mov_b32_e32 v90, 0
	v_mov_b32_e32 v91, 0
	v_mov_b32_e32 v92, 0
	v_mov_b32_e32 v93, 0
	v_mov_b32_e32 v94, 0
	v_mov_b32_e32 v95, 0
	v_mov_b32_e32 v96, 0
	v_mov_b32_e32 v97, 0
	v_mov_b32_e32 v98, 0
	v_mov_b32_e32 v99, 0
	v_mov_b32_e32 v100, 0
	v_mov_b32_e32 v101, 0
	v_mov_b32_e32 v102, 0
	v_mov_b32_e32 v103, 0
	v_mov_b32_e32 v104, 0
	v_mov_b32_e32 v105, 0
	v_mov_b32_e32 v106, 0
	v_mov_b32_e32 v107, 0
	v_mov_b32_e32 v108, 0
	v_mov_b32_e32 v109, 0
	v_mov_b32_e32 v110, 0
	v_mov_b32_e32 v111, 0
	v_mov_b32_e32 v112, 0
	v_mov_b32_e32 v113, 0
	v_mov_b32_e32 v114, 0
	v_mov_b32_e32 v115, 0
	v_mov_b32_e32 v116, 0
	v_mov_b32_e32 v117, 0
	v_mov_b32_e32 v118, 0
	v_mov_b32_e32 v119, 0
	v_mov_b32_e32 v120, 0
	v_mov_b32_e32 v121, 0
	v_mov_b32_e32 v122, 0
	v_mov_b32_e32 v123, 0
	v_mov_b32_e32 v124, 0
	v_mov_b32_e32 v125, 0
	v_mov_b32_e32 v126, 0
	v_mov_b32_e32 v127, 0
	v_mov_b32_e32 v128, 0
	v_mov_b32_e32 v129, 0
	s_branch .LBB0_245

;     __device__ __forceinline__ bool next(int i, Unit& u) const { if (i >= n) return false; u.pm = pm + i * dpm; u.pn = first + i * dpn; return true; }
; #define PG8_STAGE(bufoff, gbase, voff) do { _Pragma("unroll") for (int _i = 0; _i < 2; ++_i) \
;         __builtin_amdgcn_global_load_lds((const unsigned*)((const char*)(gbase) + (voff)[_i]), (PG8_LAS unsigned*)(lds + (bufoff) + ldsw + _i * 8192), 16, 0, 0); } while (0)
; #define PG8_LDA(dst, b, h) do { _Pragma("unroll") for (int m = 0; m < 4; ++m) _Pragma("unroll") for (int k = 0; k < 2; ++k) dst[m][k] = *(const PG8_LAS bf16x8*)(lds + PG8_SA(b, h) + aoff + m * 2048 + k * 1024); } while (0)
; #define PG8_WAIT_V(n) asm volatile("s_waitcnt vmcnt(" #n ")" ::: "memory")
; #define PG8_BAR __builtin_amdgcn_s_barrier()
; template <class Epi, class Sched, bool ALIGN_EPI = false, bool SP2 = false>
; __device__ __forceinline__ void gemm_phase(PG8_LAS unsigned char* lds, const Gemm g, const Sched& S, const Epi& E) {
;     ...
;         const bool has_next = S.next(ui + 1, nxt);
;         const char* nA = has_next ? (const char*)g.A + (size_t)nxt.pm * tstep : cA; const char* nB = has_next ? (const char*)g.Bt + (size_t)nxt.pn * tstep : cB;
;         for (int t = 0; t < nt; t += 2) {
;             const bool last = (t == nt - 2);
;             const char* a1 = cA + (size_t)(t + 1) * kstep;
;             const char* a2 = last ? nA : cA + (size_t)(t + 2) * kstep; const char* b2 = last ? nB : cB + (size_t)(t + 2) * kstep;
;             const char* a3 = a2 + kstep; const char* b3 = b2 + kstep;
;             if (last && has_next) S.a_ready(nxt);
;             if constexpr (SP2) {
;             PG8_LDB(B0, 0, 0); PG8_LDB(B1, 0, 1); PG8_SCHED; PG8_LDA(At, 0, 0); PG8_STAGE(PG8_SA(1, 1), a1 + hstep, voffA);
;             PG8_WAIT_V(8); PG8_WAIT_L(0); PG8_BAR; PG8_MMA(0, 0, At, B0); PG8_MMA(0, 1, At, B1); PG8_BAR; PG8_SCHED;
;             PG8_LDA(At, 0, 1); PG8_STAGE(PG8_SB(0, 0), b2, voffB); PG8_STAGE(PG8_SB(0, 1), b2 + hstep, voffB); PG8_STAGE(PG8_SA(0, 0), a2, voffA);
;             PG8_WAIT_V(8); PG8_WAIT_L(0); PG8_BAR; PG8_MMA(1, 0, At, B0); PG8_MMA(1, 1, At, B1); PG8_BAR; PG8_SCHED;
;             PG8_LDB(B0, 1, 0); PG8_LDB(B1, 1, 1); PG8_SCHED; PG8_LDA(At, 1, 0); PG8_STAGE(PG8_SA(0, 1), a2 + hstep, voffA);
;             PG8_WAIT_V(8); PG8_WAIT_L(0); PG8_BAR; PG8_MMA(0, 0, At, B0); PG8_MMA(0, 1, At, B1); PG8_BAR; PG8_SCHED;
.LBB0_251:
	s_ashr_i32 s61, s60, 31
	s_lshl_b64 s[62:63], s[60:61], 19
	s_add_u32 s62, s51, s62
	s_addc_u32 s63, s80, s63
	s_and_b64 s[64:65], s[0:1], exec
	s_cselect_b32 s45, s63, s57
	s_cselect_b32 s61, s62, s56
	s_ashr_i32 s53, s52, 31
	s_lshl_b64 s[64:65], s[52:53], 19
	s_add_u32 s64, s82, s64
	s_addc_u32 s65, s83, s65
	s_and_b64 s[66:67], s[0:1], exec
	s_cselect_b32 s53, s65, s59
	s_cselect_b32 vcc_lo, s64, s58
	s_add_u32 s56, s56, 0x40080
	s_addc_u32 s57, s57, 0
	s_add_u32 vcc_hi, s58, 0x100
	v_mov_b32_e32 v2, 0
	s_addc_u32 s2, s59, 0
	s_mov_b32 s10, -2
.LBB0_252:
	s_add_u32 s12, s56, 0xfffc0080
	s_addc_u32 s13, s57, -1
	s_add_i32 s14, 0, 0x10000
	s_cmp_eq_u32 s10, 12
	s_cselect_b32 s67, s45, s13
	s_cselect_b32 s66, s61, s12
	v_add_u32_e32 v152, s14, v133
	s_cselect_b32 s59, s53, s2
	s_cselect_b32 s58, vcc_lo, vcc_hi
	s_add_i32 s15, 0, 0x14000
	ds_read_b128 v[162:165], v152
	ds_read_b128 v[166:169], v152 offset:1024
	ds_read_b128 v[170:173], v152 offset:2048
	ds_read_b128 v[174:177], v152 offset:3072
	v_add_u32_e32 v152, s15, v133
	ds_read_b128 v[178:181], v152
	ds_read_b128 v[182:185], v152 offset:1024
	ds_read_b128 v[186:189], v152 offset:2048
	ds_read_b128 v[190:193], v152 offset:3072
	v_lshl_add_u64 v[152:153], s[56:57], 0, v[148:149]
	s_add_i32 m0, s11, 0xc000
	ds_read_b128 v[194:197], v158
	ds_read_b128 v[198:201], v158 offset:1024
	ds_read_b128 v[202:205], v158 offset:2048
	ds_read_b128 v[206:209], v158 offset:3072
	ds_read_b128 v[210:213], v158 offset:4096
	ds_read_b128 v[214:217], v158 offset:5120
	ds_read_b128 v[218:221], v158 offset:6144
	ds_read_b128 v[222:225], v158 offset:7168
	global_load_lds_dwordx4 v[152:153], off
	v_lshl_add_u64 v[152:153], s[56:57], 0, v[150:151]
	s_add_i32 m0, s11, 0xe000
	s_nop 0
	global_load_lds_dwordx4 v[152:153], off
	s_waitcnt vmcnt(8)
	s_waitcnt lgkmcnt(0)
	s_barrier
	s_setprio 1
	s_waitcnt lgkmcnt(0)
	v_mfma_f32_16x16x32_bf16 v[126:129], v[162:165], v[194:197], v[126:129]
	v_mfma_f32_16x16x32_bf16 v[122:125], v[170:173], v[194:197], v[122:125]
	v_mfma_f32_16x16x32_bf16 v[114:117], v[162:165], v[202:205], v[114:117]
	v_mfma_f32_16x16x32_bf16 v[106:109], v[170:173], v[202:205], v[106:109]
	v_mfma_f32_16x16x32_bf16 v[98:101], v[162:165], v[210:213], v[98:101]
	v_mfma_f32_16x16x32_bf16 v[90:93], v[170:173], v[210:213], v[90:93]
	v_mfma_f32_16x16x32_bf16 v[82:85], v[162:165], v[218:221], v[82:85]
	v_mfma_f32_16x16x32_bf16 v[74:77], v[170:173], v[218:221], v[74:77]
	v_mfma_f32_16x16x32_bf16 v[126:129], v[166:169], v[198:201], v[126:129]
	v_mfma_f32_16x16x32_bf16 v[122:125], v[174:177], v[198:201], v[122:125]
	v_mfma_f32_16x16x32_bf16 v[114:117], v[166:169], v[206:209], v[114:117]
	v_mfma_f32_16x16x32_bf16 v[106:109], v[174:177], v[206:209], v[106:109]
	v_mfma_f32_16x16x32_bf16 v[98:101], v[166:169], v[214:217], v[98:101]
	v_mfma_f32_16x16x32_bf16 v[90:93], v[174:177], v[214:217], v[90:93]
	v_mfma_f32_16x16x32_bf16 v[82:85], v[166:169], v[222:225], v[82:85]
	v_mfma_f32_16x16x32_bf16 v[74:77], v[174:177], v[222:225], v[74:77]
	s_setprio 0
	s_setprio 1
	v_mfma_f32_16x16x32_bf16 v[118:121], v[178:181], v[194:197], v[118:121]
	v_mfma_f32_16x16x32_bf16 v[110:113], v[186:189], v[194:197], v[110:113]
	v_mfma_f32_16x16x32_bf16 v[102:105], v[178:181], v[202:205], v[102:105]
	v_mfma_f32_16x16x32_bf16 v[94:97], v[186:189], v[202:205], v[94:97]
	v_mfma_f32_16x16x32_bf16 v[86:89], v[178:181], v[210:213], v[86:89]
	v_mfma_f32_16x16x32_bf16 v[78:81], v[186:189], v[210:213], v[78:81]
	v_mfma_f32_16x16x32_bf16 v[70:73], v[178:181], v[218:221], v[70:73]
	v_mfma_f32_16x16x32_bf16 v[66:69], v[186:189], v[218:221], v[66:69]
	v_mfma_f32_16x16x32_bf16 v[118:121], v[182:185], v[198:201], v[118:121]
	v_mfma_f32_16x16x32_bf16 v[110:113], v[190:193], v[198:201], v[110:113]
	v_mfma_f32_16x16x32_bf16 v[102:105], v[182:185], v[206:209], v[102:105]
	v_mfma_f32_16x16x32_bf16 v[94:97], v[190:193], v[206:209], v[94:97]
	v_mfma_f32_16x16x32_bf16 v[86:89], v[182:185], v[214:217], v[86:89]
	v_mfma_f32_16x16x32_bf16 v[78:81], v[190:193], v[214:217], v[78:81]
	v_mfma_f32_16x16x32_bf16 v[70:73], v[182:185], v[222:225], v[70:73]
	v_mfma_f32_16x16x32_bf16 v[66:69], v[190:193], v[222:225], v[66:69]
	s_setprio 0
	s_barrier
	s_add_i32 s12, s14, s50
	v_lshl_add_u64 v[152:153], s[58:59], 0, v[130:131]
	s_mov_b32 m0, s12
	ds_read_b128 v[194:197], v158 offset:16384
	ds_read_b128 v[198:201], v158 offset:17408
	ds_read_b128 v[202:205], v158 offset:18432
	ds_read_b128 v[206:209], v158 offset:19456
	ds_read_b128 v[210:213], v158 offset:20480
	ds_read_b128 v[214:217], v158 offset:21504
	ds_read_b128 v[218:221], v158 offset:22528
	ds_read_b128 v[222:225], v158 offset:23552
	global_load_lds_dwordx4 v[152:153], off
	s_add_i32 m0, s12, 0x2000
	s_add_u32 s12, s58, 0x40000
	v_lshl_add_u64 v[226:227], s[58:59], 0, v[142:143]
	s_addc_u32 s13, s59, 0
	s_add_i32 s14, s15, s50
	global_load_lds_dwordx4 v[226:227], off
	v_lshl_add_u64 v[228:229], s[12:13], 0, v[130:131]
	s_mov_b32 m0, s14
	v_lshl_add_u64 v[230:231], s[66:67], 0, v[144:145]
	global_load_lds_dwordx4 v[228:229], off
	v_lshl_add_u64 v[228:229], s[12:13], 0, v[142:143]
	s_add_i32 m0, s14, 0x2000
	s_nop 0
	global_load_lds_dwordx4 v[228:229], off
	v_lshl_add_u64 v[228:229], s[66:67], 0, v[146:147]
	s_mov_b32 m0, s11
	s_nop 0
	global_load_lds_dwordx4 v[228:229], off
	s_mov_b32 m0, s30
	s_nop 0
	global_load_lds_dwordx4 v[230:231], off
	s_waitcnt vmcnt(8)
	s_waitcnt lgkmcnt(0)
	s_barrier
; #define PG8_STAGE(bufoff, gbase, voff) do { _Pragma("unroll") for (int _i = 0; _i < 2; ++_i) \
;         __builtin_amdgcn_global_load_lds((const unsigned*)((const char*)(gbase) + (voff)[_i]), (PG8_LAS unsigned*)(lds + (bufoff) + ldsw + _i * 8192), 16, 0, 0); } while (0)
; #define PG8_LDA(dst, b, h) do { _Pragma("unroll") for (int m = 0; m < 4; ++m) _Pragma("unroll") for (int k = 0; k < 2; ++k) dst[m][k] = *(const PG8_LAS bf16x8*)(lds + PG8_SA(b, h) + aoff + m * 2048 + k * 1024); } while (0)
; #define PG8_LDB(dst, b, h) do { _Pragma("unroll") for (int n = 0; n < 2; ++n) _Pragma("unroll") for (int k = 0; k < 2; ++k) dst[n][k] = *(const PG8_LAS bf16x8*)(lds + PG8_SB(b, h) + boff + n * 2048 + k * 1024); } while (0)
; #define PG8_MMA(ai, bj, At, Bt) do { __builtin_amdgcn_s_setprio(1); _Pragma("unroll") for (int m = 0; m < 4; ++m) _Pragma("unroll") for (int n = 0; n < 2; ++n) _Pragma("unroll") for (int k = 0; k < 2; ++k) \
;         acc[ai][bj][m][n] = __builtin_amdgcn_mfma_f32_16x16x32_bf16(Bt[n][k], At[m][k], acc[ai][bj][m][n], 0, 0, 0); __builtin_amdgcn_s_setprio(0); } while (0)
; #define PG8_WAIT_V(n) asm volatile("s_waitcnt vmcnt(" #n ")" ::: "memory")
; #define PG8_WAIT_L(n) asm volatile("s_waitcnt lgkmcnt(" #n ")" ::: "memory")
; #define PG8_BAR __builtin_amdgcn_s_barrier()
; #define PG8_SCHED __builtin_amdgcn_sched_barrier(0)
; template <class Epi, class Sched, bool ALIGN_EPI = false, bool SP2 = false>
; __device__ __forceinline__ void gemm_phase(PG8_LAS unsigned char* lds, const Gemm g, const Sched& S, const Epi& E) {
;     ...
;             PG8_WAIT_V(8); PG8_WAIT_L(0); PG8_BAR; PG8_MMA(0, 0, At, B0); PG8_MMA(0, 1, At, B1); PG8_BAR; PG8_SCHED;
;             PG8_LDA(At, 0, 1); PG8_STAGE(PG8_SB(0, 0), b2, voffB); PG8_STAGE(PG8_SB(0, 1), b2 + hstep, voffB); PG8_STAGE(PG8_SA(0, 0), a2, voffA);
;             PG8_WAIT_V(8); PG8_WAIT_L(0); PG8_BAR; PG8_MMA(1, 0, At, B0); PG8_MMA(1, 1, At, B1); PG8_BAR; PG8_SCHED;
;             PG8_LDB(B0, 1, 0); PG8_LDB(B1, 1, 1); PG8_SCHED; PG8_LDA(At, 1, 0); PG8_STAGE(PG8_SA(0, 1), a2 + hstep, voffA);
;             PG8_WAIT_V(8); PG8_WAIT_L(0); PG8_BAR; PG8_MMA(0, 0, At, B0); PG8_MMA(0, 1, At, B1); PG8_BAR; PG8_SCHED;
	s_setprio 1
	s_waitcnt lgkmcnt(0)
	v_mfma_f32_16x16x32_bf16 v[62:65], v[162:165], v[194:197], v[62:65]
	v_mfma_f32_16x16x32_bf16 v[58:61], v[170:173], v[194:197], v[58:61]
	v_mfma_f32_16x16x32_bf16 v[50:53], v[162:165], v[202:205], v[50:53]
	v_mfma_f32_16x16x32_bf16 v[42:45], v[170:173], v[202:205], v[42:45]
	v_mfma_f32_16x16x32_bf16 v[34:37], v[162:165], v[210:213], v[34:37]
	v_mfma_f32_16x16x32_bf16 v[26:29], v[170:173], v[210:213], v[26:29]
	v_mfma_f32_16x16x32_bf16 v[18:21], v[162:165], v[218:221], v[18:21]
	v_mfma_f32_16x16x32_bf16 v[10:13], v[170:173], v[218:221], v[10:13]
	v_mfma_f32_16x16x32_bf16 v[62:65], v[166:169], v[198:201], v[62:65]
	v_mfma_f32_16x16x32_bf16 v[58:61], v[174:177], v[198:201], v[58:61]
	v_mfma_f32_16x16x32_bf16 v[50:53], v[166:169], v[206:209], v[50:53]
	v_mfma_f32_16x16x32_bf16 v[42:45], v[174:177], v[206:209], v[42:45]
	v_mfma_f32_16x16x32_bf16 v[34:37], v[166:169], v[214:217], v[34:37]
	v_mfma_f32_16x16x32_bf16 v[26:29], v[174:177], v[214:217], v[26:29]
	v_mfma_f32_16x16x32_bf16 v[18:21], v[166:169], v[222:225], v[18:21]
	v_mfma_f32_16x16x32_bf16 v[10:13], v[174:177], v[222:225], v[10:13]
	s_setprio 0
	s_setprio 1
	v_mfma_f32_16x16x32_bf16 v[54:57], v[178:181], v[194:197], v[54:57]
	v_mfma_f32_16x16x32_bf16 v[46:49], v[186:189], v[194:197], v[46:49]
	v_mfma_f32_16x16x32_bf16 v[38:41], v[178:181], v[202:205], v[38:41]
	v_mfma_f32_16x16x32_bf16 v[30:33], v[186:189], v[202:205], v[30:33]
	v_mfma_f32_16x16x32_bf16 v[22:25], v[178:181], v[210:213], v[22:25]
	v_mfma_f32_16x16x32_bf16 v[14:17], v[186:189], v[210:213], v[14:17]
	v_mfma_f32_16x16x32_bf16 v[6:9], v[178:181], v[218:221], v[6:9]
	v_mfma_f32_16x16x32_bf16 v[2:5], v[186:189], v[218:221], v[2:5]
	v_mfma_f32_16x16x32_bf16 v[54:57], v[182:185], v[198:201], v[54:57]
	v_mfma_f32_16x16x32_bf16 v[46:49], v[190:193], v[198:201], v[46:49]
	v_mfma_f32_16x16x32_bf16 v[38:41], v[182:185], v[206:209], v[38:41]
	v_mfma_f32_16x16x32_bf16 v[30:33], v[190:193], v[206:209], v[30:33]
	v_mfma_f32_16x16x32_bf16 v[22:25], v[182:185], v[214:217], v[22:25]
	v_mfma_f32_16x16x32_bf16 v[14:17], v[190:193], v[214:217], v[14:17]
	v_mfma_f32_16x16x32_bf16 v[6:9], v[182:185], v[222:225], v[6:9]
	v_mfma_f32_16x16x32_bf16 v[2:5], v[190:193], v[222:225], v[2:5]
	s_setprio 0
	s_barrier
	s_add_i32 s14, 0, 0x18000
	v_add_u32_e32 v161, s14, v133
	s_add_i32 s15, 0, 0x1c000
	ds_read_b128 v[162:165], v161
	ds_read_b128 v[166:169], v161 offset:1024
	ds_read_b128 v[170:173], v161 offset:2048
	ds_read_b128 v[174:177], v161 offset:3072
	v_add_u32_e32 v161, s15, v133
	ds_read_b128 v[178:181], v161
	ds_read_b128 v[182:185], v161 offset:1024
	ds_read_b128 v[186:189], v161 offset:2048
	ds_read_b128 v[190:193], v161 offset:3072
	s_add_u32 s12, s66, 0x40000
	s_addc_u32 s13, s67, 0
	s_mov_b32 m0, s31
	v_lshl_add_u64 v[232:233], s[12:13], 0, v[146:147]
	ds_read_b128 v[194:197], v158 offset:32768
	ds_read_b128 v[198:201], v158 offset:33792
	ds_read_b128 v[202:205], v158 offset:34816
	ds_read_b128 v[206:209], v158 offset:35840
	ds_read_b128 v[210:213], v158 offset:36864
	ds_read_b128 v[214:217], v158 offset:37888
	ds_read_b128 v[218:221], v158 offset:38912
	ds_read_b128 v[222:225], v158 offset:39936
	global_load_lds_dwordx4 v[232:233], off
	v_lshl_add_u64 v[232:233], s[12:13], 0, v[144:145]
	s_mov_b32 m0, s86
	s_nop 0
	global_load_lds_dwordx4 v[232:233], off
	s_waitcnt vmcnt(8)
	s_waitcnt lgkmcnt(0)
	s_barrier
	s_setprio 1
	s_waitcnt lgkmcnt(0)
	v_mfma_f32_16x16x32_bf16 v[126:129], v[162:165], v[194:197], v[126:129]
	v_mfma_f32_16x16x32_bf16 v[122:125], v[170:173], v[194:197], v[122:125]
	v_mfma_f32_16x16x32_bf16 v[114:117], v[162:165], v[202:205], v[114:117]
	v_mfma_f32_16x16x32_bf16 v[106:109], v[170:173], v[202:205], v[106:109]
	v_mfma_f32_16x16x32_bf16 v[98:101], v[162:165], v[210:213], v[98:101]
	v_mfma_f32_16x16x32_bf16 v[90:93], v[170:173], v[210:213], v[90:93]
	v_mfma_f32_16x16x32_bf16 v[82:85], v[162:165], v[218:221], v[82:85]
	v_mfma_f32_16x16x32_bf16 v[74:77], v[170:173], v[218:221], v[74:77]
	v_mfma_f32_16x16x32_bf16 v[126:129], v[166:169], v[198:201], v[126:129]
	v_mfma_f32_16x16x32_bf16 v[122:125], v[174:177], v[198:201], v[122:125]
	v_mfma_f32_16x16x32_bf16 v[114:117], v[166:169], v[206:209], v[114:117]
	v_mfma_f32_16x16x32_bf16 v[106:109], v[174:177], v[206:209], v[106:109]
	v_mfma_f32_16x16x32_bf16 v[98:101], v[166:169], v[214:217], v[98:101]
	v_mfma_f32_16x16x32_bf16 v[90:93], v[174:177], v[214:217], v[90:93]
	v_mfma_f32_16x16x32_bf16 v[82:85], v[166:169], v[222:225], v[82:85]
	v_mfma_f32_16x16x32_bf16 v[74:77], v[174:177], v[222:225], v[74:77]
	s_setprio 0
	s_setprio 1
	v_mfma_f32_16x16x32_bf16 v[118:121], v[178:181], v[194:197], v[118:121]
	v_mfma_f32_16x16x32_bf16 v[110:113], v[186:189], v[194:197], v[110:113]
	v_mfma_f32_16x16x32_bf16 v[102:105], v[178:181], v[202:205], v[102:105]
	v_mfma_f32_16x16x32_bf16 v[94:97], v[186:189], v[202:205], v[94:97]
	v_mfma_f32_16x16x32_bf16 v[86:89], v[178:181], v[210:213], v[86:89]
	v_mfma_f32_16x16x32_bf16 v[78:81], v[186:189], v[210:213], v[78:81]
	v_mfma_f32_16x16x32_bf16 v[70:73], v[178:181], v[218:221], v[70:73]
	v_mfma_f32_16x16x32_bf16 v[66:69], v[186:189], v[218:221], v[66:69]
	v_mfma_f32_16x16x32_bf16 v[118:121], v[182:185], v[198:201], v[118:121]
	v_mfma_f32_16x16x32_bf16 v[110:113], v[190:193], v[198:201], v[110:113]
	v_mfma_f32_16x16x32_bf16 v[102:105], v[182:185], v[206:209], v[102:105]
	v_mfma_f32_16x16x32_bf16 v[94:97], v[190:193], v[206:209], v[94:97]
	v_mfma_f32_16x16x32_bf16 v[86:89], v[182:185], v[214:217], v[86:89]
	v_mfma_f32_16x16x32_bf16 v[78:81], v[190:193], v[214:217], v[78:81]
	v_mfma_f32_16x16x32_bf16 v[70:73], v[182:185], v[222:225], v[70:73]
	v_mfma_f32_16x16x32_bf16 v[66:69], v[190:193], v[222:225], v[66:69]
	s_setprio 0
	s_barrier
; #define PG8_STAGE(bufoff, gbase, voff) do { _Pragma("unroll") for (int _i = 0; _i < 2; ++_i) \
;         __builtin_amdgcn_global_load_lds((const unsigned*)((const char*)(gbase) + (voff)[_i]), (PG8_LAS unsigned*)(lds + (bufoff) + ldsw + _i * 8192), 16, 0, 0); } while (0)
; #define PG8_LDA(dst, b, h) do { _Pragma("unroll") for (int m = 0; m < 4; ++m) _Pragma("unroll") for (int k = 0; k < 2; ++k) dst[m][k] = *(const PG8_LAS bf16x8*)(lds + PG8_SA(b, h) + aoff + m * 2048 + k * 1024); } while (0)
; #define PG8_WAIT_V(n) asm volatile("s_waitcnt vmcnt(" #n ")" ::: "memory")
; template <class Epi, class Sched, bool ALIGN_EPI = false, bool SP2 = false>
; __device__ __forceinline__ void gemm_phase(PG8_LAS unsigned char* lds, const Gemm g, const Sched& S, const Epi& E) {
;     ...
;             PG8_LDA(At, 1, 1); PG8_STAGE(PG8_SB(1, 0), b3, voffB); PG8_STAGE(PG8_SB(1, 1), b3 + hstep, voffB); PG8_STAGE(PG8_SA(1, 0), a3, voffA);
;             PG8_WAIT_V(8); PG8_WAIT_L(0); PG8_BAR; PG8_MMA(1, 0, At, B0); PG8_MMA(1, 1, At, B1); PG8_BAR; PG8_SCHED;
;             } else {
;             PG8_LDB(B0, 0, 0); PG8_SCHED; PG8_LDA(At, 0, 0); PG8_STAGE(PG8_SA(1, 1), a1 + hstep, voffA);
;             PG8_WAIT_L(8); PG8_BAR; PG8_WAIT_L(0); PG8_MMA(0, 0, At, B0); PG8_BAR; PG8_SCHED;
;             PG8_LDB(B1, 0, 1); PG8_STAGE(PG8_SB(0, 0), b2, voffB);
;             PG8_BAR; PG8_WAIT_L(0); PG8_MMA(0, 1, At, B1); PG8_BAR;
;             PG8_LDA(At, 0, 1); PG8_STAGE(PG8_SA(0, 0), a2, voffA);
;             PG8_BAR; PG8_WAIT_L(0); PG8_MMA(1, 0, At, B0); PG8_BAR; PG8_SCHED;
;             PG8_STAGE(PG8_SB(0, 1), b2 + hstep, voffB);
;             PG8_WAIT_V(6); PG8_BAR; PG8_MMA(1, 1, At, B1); PG8_BAR;
;             PG8_LDB(B0, 1, 0); PG8_SCHED; PG8_LDA(At, 1, 0); PG8_STAGE(PG8_SA(0, 1), a2 + hstep, voffA);
;             PG8_WAIT_L(8); PG8_BAR; PG8_WAIT_L(0); PG8_MMA(0, 0, At, B0); PG8_BAR; PG8_SCHED;
;             PG8_LDB(B1, 1, 1); PG8_STAGE(PG8_SB(1, 0), b3, voffB);
;             PG8_BAR; PG8_WAIT_L(0); PG8_MMA(0, 1, At, B1); PG8_BAR;
;             PG8_LDA(At, 1, 1); PG8_STAGE(PG8_SA(1, 0), a3, voffA);
;             PG8_BAR; PG8_WAIT_L(0); PG8_MMA(1, 0, At, B0); PG8_BAR; PG8_SCHED;
;             PG8_STAGE(PG8_SB(1, 1), b3 + hstep, voffB);
;             PG8_WAIT_V(6); PG8_BAR; PG8_MMA(1, 1, At, B1); PG8_BAR;
;             }
;         }
;         if constexpr (ALIGN_EPI) { if (wr == 0) PG8_BAR; }
	s_add_i32 s12, s14, s50
	v_lshl_add_u64 v[152:153], v[152:153], 0, s[46:47]
	s_mov_b32 m0, s12
	ds_read_b128 v[194:197], v158 offset:49152
	ds_read_b128 v[198:201], v158 offset:50176
	ds_read_b128 v[202:205], v158 offset:51200
	ds_read_b128 v[206:209], v158 offset:52224
	ds_read_b128 v[210:213], v158 offset:53248
	ds_read_b128 v[214:217], v158 offset:54272
	ds_read_b128 v[218:221], v158 offset:55296
	ds_read_b128 v[222:225], v158 offset:56320
	global_load_lds_dwordx4 v[152:153], off
	s_add_i32 m0, s12, 0x2000
	s_add_u32 s12, s58, 0x40080
	v_lshl_add_u64 v[152:153], v[226:227], 0, s[46:47]
	s_addc_u32 s13, s59, 0
	s_add_i32 s14, s15, s50
	global_load_lds_dwordx4 v[152:153], off
	v_lshl_add_u64 v[152:153], s[12:13], 0, v[130:131]
	s_mov_b32 m0, s14
	s_nop 0
	global_load_lds_dwordx4 v[152:153], off
	v_lshl_add_u64 v[152:153], s[12:13], 0, v[142:143]
	s_add_i32 m0, s14, 0x2000
	s_nop 0
	global_load_lds_dwordx4 v[152:153], off
	v_lshl_add_u64 v[152:153], v[228:229], 0, s[46:47]
	s_mov_b32 m0, s38
	s_nop 0
	global_load_lds_dwordx4 v[152:153], off
	v_lshl_add_u64 v[152:153], v[230:231], 0, s[46:47]
	s_mov_b32 m0, s39
	s_nop 0
	global_load_lds_dwordx4 v[152:153], off
	s_waitcnt vmcnt(8)
	s_waitcnt lgkmcnt(0)
	s_barrier
	s_setprio 1
	s_waitcnt lgkmcnt(0)
	v_mfma_f32_16x16x32_bf16 v[62:65], v[162:165], v[194:197], v[62:65]
	v_mfma_f32_16x16x32_bf16 v[58:61], v[170:173], v[194:197], v[58:61]
	v_mfma_f32_16x16x32_bf16 v[50:53], v[162:165], v[202:205], v[50:53]
	v_mfma_f32_16x16x32_bf16 v[42:45], v[170:173], v[202:205], v[42:45]
	v_mfma_f32_16x16x32_bf16 v[34:37], v[162:165], v[210:213], v[34:37]
	v_mfma_f32_16x16x32_bf16 v[26:29], v[170:173], v[210:213], v[26:29]
	v_mfma_f32_16x16x32_bf16 v[18:21], v[162:165], v[218:221], v[18:21]
	v_mfma_f32_16x16x32_bf16 v[10:13], v[170:173], v[218:221], v[10:13]
	v_mfma_f32_16x16x32_bf16 v[62:65], v[166:169], v[198:201], v[62:65]
	v_mfma_f32_16x16x32_bf16 v[58:61], v[174:177], v[198:201], v[58:61]
	v_mfma_f32_16x16x32_bf16 v[50:53], v[166:169], v[206:209], v[50:53]
	v_mfma_f32_16x16x32_bf16 v[42:45], v[174:177], v[206:209], v[42:45]
	v_mfma_f32_16x16x32_bf16 v[34:37], v[166:169], v[214:217], v[34:37]
	v_mfma_f32_16x16x32_bf16 v[26:29], v[174:177], v[214:217], v[26:29]
	v_mfma_f32_16x16x32_bf16 v[18:21], v[166:169], v[222:225], v[18:21]
	v_mfma_f32_16x16x32_bf16 v[10:13], v[174:177], v[222:225], v[10:13]
	s_setprio 0
	s_setprio 1
	v_mfma_f32_16x16x32_bf16 v[54:57], v[178:181], v[194:197], v[54:57]
	v_mfma_f32_16x16x32_bf16 v[46:49], v[186:189], v[194:197], v[46:49]
	v_mfma_f32_16x16x32_bf16 v[38:41], v[178:181], v[202:205], v[38:41]
	v_mfma_f32_16x16x32_bf16 v[30:33], v[186:189], v[202:205], v[30:33]
	v_mfma_f32_16x16x32_bf16 v[22:25], v[178:181], v[210:213], v[22:25]
	v_mfma_f32_16x16x32_bf16 v[14:17], v[186:189], v[210:213], v[14:17]
	v_mfma_f32_16x16x32_bf16 v[6:9], v[178:181], v[218:221], v[6:9]
	v_mfma_f32_16x16x32_bf16 v[2:5], v[186:189], v[218:221], v[2:5]
	v_mfma_f32_16x16x32_bf16 v[54:57], v[182:185], v[198:201], v[54:57]
	v_mfma_f32_16x16x32_bf16 v[46:49], v[190:193], v[198:201], v[46:49]
	v_mfma_f32_16x16x32_bf16 v[38:41], v[182:185], v[206:209], v[38:41]
	v_mfma_f32_16x16x32_bf16 v[30:33], v[190:193], v[206:209], v[30:33]
	v_mfma_f32_16x16x32_bf16 v[22:25], v[182:185], v[214:217], v[22:25]
	v_mfma_f32_16x16x32_bf16 v[14:17], v[190:193], v[214:217], v[14:17]
	v_mfma_f32_16x16x32_bf16 v[6:9], v[182:185], v[222:225], v[6:9]
	v_mfma_f32_16x16x32_bf16 v[2:5], v[190:193], v[222:225], v[2:5]
	s_setprio 0
	s_barrier
	s_add_i32 s10, s10, 2
	s_add_u32 s56, s56, 0x100
	s_addc_u32 s57, s57, 0
	s_add_u32 vcc_hi, vcc_hi, 0x100
	s_addc_u32 s2, s2, 0
	s_cmp_gt_u32 s10, 13
	s_cbranch_scc0 .LBB0_252
	s_and_b64 vcc, exec, s[48:49]
	s_cbranch_vccz .LBB0_255
	s_barrier

; #define PG8_LAS __attribute__((address_space(3)))
; __device__ __forceinline__ unsigned cvt_pk_bf16(float lo, float hi) { unsigned r; asm volatile("v_cvt_pk_bf16_f32 %0, %1, %2" : "=v"(r) : "v"(lo), "v"(hi)); return r; }
;     __device__ __forceinline__ void operator()(const f32x4 (&acc)[2][2][4][2], const Unit& u_, int wr, int wc, int fr, int fq) const {
;     ...
;         const int l = fq * 16 + fr; PG8_LAS unsigned char* xl = xl0 + (wr * 4 + wc) * XCHG_WAVE_BYTES;
;         const int rowb = u.pm * BM + wr * 64 + (l >> 2); const int colb = colt + wc * 32 + 8 * (l & 3);
; #pragma unroll
;         for (int ai = 0; ai < 2; ++ai)
; #pragma unroll
;             for (int m = 0; m < 4; ++m) { bf16_t* rowp = base + (size_t)(rowb + ai * HALF + m * 16) * ldc + colb;
; #pragma unroll
;                 for (int bj = 0; bj < 2; ++bj) { const f32x4 v0 = acc[ai][bj][m][0], v1 = acc[ai][bj][m][1];
;                     u32x4 w; w.x = cvt_pk_bf16(v0[0], v0[1]); w.y = cvt_pk_bf16(v0[2], v0[3]); w.z = cvt_pk_bf16(v1[0], v1[1]); w.w = cvt_pk_bf16(v1[2], v1[3]);
;                     *(u32x4*)(rowp + bj * HALF) = xchg_bf16(xl, fr, fq, l, w); } }
; template <class Epi, class Sched, bool ALIGN_EPI = false, bool SP2 = false>
; __device__ __forceinline__ void gemm_phase(PG8_LAS unsigned char* lds, const Gemm g, const Sched& S, const Epi& E) {
;     ...
;         if constexpr (!Epi::AFTER_DRAIN) { E(acc, cur, wr, wc, fr, fq); S.done(cur); }
;         if (!has_next) break;
; #pragma unroll
;         for (int a = 0; a < 2; ++a)
; #pragma unroll
;             for (int b = 0; b < 2; ++b)
; #pragma unroll
;                 for (int m = 0; m < 4; ++m)
; #pragma unroll
;                     for (int n = 0; n < 2; ++n) acc[a][b][m][n] = (f32x4){0.f, 0.f, 0.f, 0.f};
.LBB0_263:
	v_lshl_add_u32 v161, s43, 8, v157
	v_add_u32_e32 v152, s2, v156
	v_ashrrev_i32_e32 v153, 31, v152
	v_lshl_add_u64 v[152:153], v[152:153], 1, s[58:59]
	v_mad_u64_u32 v[210:211], s[12:13], s56, v161, 0
	v_lshl_add_u64 v[210:211], v[210:211], 1, v[152:153]
	v_add_u32_e32 v226, 0x10, v161
	v_mad_u64_u32 v[212:213], s[12:13], s56, v226, 0
	v_lshl_add_u64 v[212:213], v[212:213], 1, v[152:153]
	v_add_u32_e32 v226, 0x20, v161
	v_mad_u64_u32 v[214:215], s[12:13], s56, v226, 0
	v_lshl_add_u64 v[214:215], v[214:215], 1, v[152:153]
	v_add_u32_e32 v226, 0x30, v161
	v_mad_u64_u32 v[216:217], s[12:13], s56, v226, 0
	v_lshl_add_u64 v[216:217], v[216:217], 1, v[152:153]
	v_add_u32_e32 v226, 0x80, v161
	v_mad_u64_u32 v[218:219], s[12:13], s56, v226, 0
	v_lshl_add_u64 v[218:219], v[218:219], 1, v[152:153]
	v_add_u32_e32 v226, 0x90, v161
	v_mad_u64_u32 v[220:221], s[12:13], s56, v226, 0
	v_lshl_add_u64 v[220:221], v[220:221], 1, v[152:153]
	v_add_u32_e32 v226, 0xa0, v161
	v_mad_u64_u32 v[222:223], s[12:13], s56, v226, 0
	v_lshl_add_u64 v[222:223], v[222:223], 1, v[152:153]
	v_add_u32_e32 v226, 0xb0, v161
	v_mad_u64_u32 v[224:225], s[12:13], s56, v226, 0
	v_lshl_add_u64 v[224:225], v[224:225], 1, v[152:153]
	s_andn2_b64 vcc, exec, s[0:1]
	s_mov_b64 s[0:1], -1
	v_cvt_pk_bf16_f32 v226, v126, v127
	v_cvt_pk_bf16_f32 v227, v128, v129
	v_cvt_pk_bf16_f32 v228, v122, v123
	v_cvt_pk_bf16_f32 v229, v124, v125
	ds_write_b128 v159, v[226:229]
	ds_read_b128 v[162:165], v160
	v_mov_b32_e32 v126, 0
	v_mov_b32_e32 v127, 0
	v_mov_b32_e32 v128, 0
	v_mov_b32_e32 v129, 0
	v_mov_b32_e32 v122, 0
	v_mov_b32_e32 v123, 0
	v_mov_b32_e32 v124, 0
	v_mov_b32_e32 v125, 0
	v_cvt_pk_bf16_f32 v230, v118, v119
	v_cvt_pk_bf16_f32 v231, v120, v121
	v_cvt_pk_bf16_f32 v232, v110, v111
	v_cvt_pk_bf16_f32 v233, v112, v113
	ds_write_b128 v159, v[230:233]
	ds_read_b128 v[166:169], v160
	v_mov_b32_e32 v118, 0
	v_mov_b32_e32 v119, 0
	v_mov_b32_e32 v120, 0
	v_mov_b32_e32 v121, 0
	v_mov_b32_e32 v110, 0
	v_mov_b32_e32 v111, 0
	v_mov_b32_e32 v112, 0
	v_mov_b32_e32 v113, 0
	v_cvt_pk_bf16_f32 v226, v114, v115
	v_cvt_pk_bf16_f32 v227, v116, v117
	v_cvt_pk_bf16_f32 v228, v106, v107
	v_cvt_pk_bf16_f32 v229, v108, v109
	ds_write_b128 v159, v[226:229]
	ds_read_b128 v[170:173], v160
	v_mov_b32_e32 v114, 0
	v_mov_b32_e32 v115, 0
	v_mov_b32_e32 v116, 0
	v_mov_b32_e32 v117, 0
	v_mov_b32_e32 v106, 0
	v_mov_b32_e32 v107, 0
	v_mov_b32_e32 v108, 0
	v_mov_b32_e32 v109, 0
	v_cvt_pk_bf16_f32 v230, v102, v103
	v_cvt_pk_bf16_f32 v231, v104, v105
	v_cvt_pk_bf16_f32 v232, v94, v95
	v_cvt_pk_bf16_f32 v233, v96, v97
	ds_write_b128 v159, v[230:233]
	ds_read_b128 v[174:177], v160
	v_mov_b32_e32 v102, 0
	v_mov_b32_e32 v103, 0
	v_mov_b32_e32 v104, 0
	v_mov_b32_e32 v105, 0
	v_mov_b32_e32 v94, 0
	v_mov_b32_e32 v95, 0
	v_mov_b32_e32 v96, 0
	v_mov_b32_e32 v97, 0
	s_waitcnt lgkmcnt(6)
	global_store_dwordx4 v[210:211], v[162:165], off nt
	v_cvt_pk_bf16_f32 v226, v98, v99
	v_cvt_pk_bf16_f32 v227, v100, v101
	v_cvt_pk_bf16_f32 v228, v90, v91
	v_cvt_pk_bf16_f32 v229, v92, v93
	ds_write_b128 v159, v[226:229]
	ds_read_b128 v[178:181], v160
	v_mov_b32_e32 v98, 0
	v_mov_b32_e32 v99, 0
	v_mov_b32_e32 v100, 0
	v_mov_b32_e32 v101, 0
	v_mov_b32_e32 v90, 0
	v_mov_b32_e32 v91, 0
	v_mov_b32_e32 v92, 0
	v_mov_b32_e32 v93, 0
	s_waitcnt lgkmcnt(6)
	global_store_dwordx4 v[210:211], v[166:169], off offset:256 nt
	v_cvt_pk_bf16_f32 v230, v86, v87
	v_cvt_pk_bf16_f32 v231, v88, v89
	v_cvt_pk_bf16_f32 v232, v78, v79
	v_cvt_pk_bf16_f32 v233, v80, v81
	ds_write_b128 v159, v[230:233]
	ds_read_b128 v[182:185], v160
	v_mov_b32_e32 v86, 0
	v_mov_b32_e32 v87, 0
	v_mov_b32_e32 v88, 0
	v_mov_b32_e32 v89, 0
	v_mov_b32_e32 v78, 0
	v_mov_b32_e32 v79, 0
	v_mov_b32_e32 v80, 0
	v_mov_b32_e32 v81, 0
	s_waitcnt lgkmcnt(6)
	global_store_dwordx4 v[212:213], v[170:173], off nt
	v_cvt_pk_bf16_f32 v226, v82, v83
	v_cvt_pk_bf16_f32 v227, v84, v85
	v_cvt_pk_bf16_f32 v228, v74, v75
	v_cvt_pk_bf16_f32 v229, v76, v77
	ds_write_b128 v159, v[226:229]
	ds_read_b128 v[186:189], v160
	v_mov_b32_e32 v82, 0
	v_mov_b32_e32 v83, 0
	v_mov_b32_e32 v84, 0
	v_mov_b32_e32 v85, 0
	v_mov_b32_e32 v74, 0
	v_mov_b32_e32 v75, 0
	v_mov_b32_e32 v76, 0
	v_mov_b32_e32 v77, 0
	s_waitcnt lgkmcnt(6)
; __device__ __forceinline__ unsigned cvt_pk_bf16(float lo, float hi) { unsigned r; asm volatile("v_cvt_pk_bf16_f32 %0, %1, %2" : "=v"(r) : "v"(lo), "v"(hi)); return r; }
; #define PG8_BAR __builtin_amdgcn_s_barrier()
;     __device__ __forceinline__ void operator()(const f32x4 (&acc)[2][2][4][2], const Unit& u_, int wr, int wc, int fr, int fq) const {
;     ...
;             for (int m = 0; m < 4; ++m) { bf16_t* rowp = base + (size_t)(rowb + ai * HALF + m * 16) * ldc + colb;
; #pragma unroll
;                 for (int bj = 0; bj < 2; ++bj) { const f32x4 v0 = acc[ai][bj][m][0], v1 = acc[ai][bj][m][1];
;                     u32x4 w; w.x = cvt_pk_bf16(v0[0], v0[1]); w.y = cvt_pk_bf16(v0[2], v0[3]); w.z = cvt_pk_bf16(v1[0], v1[1]); w.w = cvt_pk_bf16(v1[2], v1[3]);
;                     *(u32x4*)(rowp + bj * HALF) = xchg_bf16(xl, fr, fq, l, w); } }
; template <class Epi, class Sched, bool ALIGN_EPI = false, bool SP2 = false>
; __device__ __forceinline__ void gemm_phase(PG8_LAS unsigned char* lds, const Gemm g, const Sched& S, const Epi& E) {
;     ...
;         if constexpr (!Epi::AFTER_DRAIN) { E(acc, cur, wr, wc, fr, fq); S.done(cur); }
;         if (!has_next) break;
; #pragma unroll
;         for (int a = 0; a < 2; ++a)
; #pragma unroll
;             for (int b = 0; b < 2; ++b)
; #pragma unroll
;                 for (int m = 0; m < 4; ++m)
; #pragma unroll
;                     for (int n = 0; n < 2; ++n) acc[a][b][m][n] = (f32x4){0.f, 0.f, 0.f, 0.f};
;         cur = nxt; cA = nA; cB = nB; ++ui;
;         if constexpr (ALIGN_EPI) { if (wr == 1) PG8_BAR; }
;     }
	global_store_dwordx4 v[212:213], v[174:177], off offset:256 nt
	v_cvt_pk_bf16_f32 v230, v70, v71
	v_cvt_pk_bf16_f32 v231, v72, v73
	v_cvt_pk_bf16_f32 v232, v66, v67
	v_cvt_pk_bf16_f32 v233, v68, v69
	ds_write_b128 v159, v[230:233]
	ds_read_b128 v[190:193], v160
	v_mov_b32_e32 v70, 0
	v_mov_b32_e32 v71, 0
	v_mov_b32_e32 v72, 0
	v_mov_b32_e32 v73, 0
	v_mov_b32_e32 v66, 0
	v_mov_b32_e32 v67, 0
	v_mov_b32_e32 v68, 0
	v_mov_b32_e32 v69, 0
	s_waitcnt lgkmcnt(6)
	global_store_dwordx4 v[214:215], v[178:181], off nt
	v_cvt_pk_bf16_f32 v226, v62, v63
	v_cvt_pk_bf16_f32 v227, v64, v65
	v_cvt_pk_bf16_f32 v228, v58, v59
	v_cvt_pk_bf16_f32 v229, v60, v61
	ds_write_b128 v159, v[226:229]
	ds_read_b128 v[194:197], v160
	v_mov_b32_e32 v62, 0
	v_mov_b32_e32 v63, 0
	v_mov_b32_e32 v64, 0
	v_mov_b32_e32 v65, 0
	v_mov_b32_e32 v58, 0
	v_mov_b32_e32 v59, 0
	v_mov_b32_e32 v60, 0
	v_mov_b32_e32 v61, 0
	s_waitcnt lgkmcnt(6)
	global_store_dwordx4 v[214:215], v[182:185], off offset:256 nt
	v_cvt_pk_bf16_f32 v230, v54, v55
	v_cvt_pk_bf16_f32 v231, v56, v57
	v_cvt_pk_bf16_f32 v232, v46, v47
	v_cvt_pk_bf16_f32 v233, v48, v49
	ds_write_b128 v159, v[230:233]
	ds_read_b128 v[198:201], v160
	v_mov_b32_e32 v54, 0
	v_mov_b32_e32 v55, 0
	v_mov_b32_e32 v56, 0
	v_mov_b32_e32 v57, 0
	v_mov_b32_e32 v46, 0
	v_mov_b32_e32 v47, 0
	v_mov_b32_e32 v48, 0
	v_mov_b32_e32 v49, 0
	s_waitcnt lgkmcnt(6)
	global_store_dwordx4 v[216:217], v[186:189], off nt
	v_cvt_pk_bf16_f32 v226, v50, v51
	v_cvt_pk_bf16_f32 v227, v52, v53
	v_cvt_pk_bf16_f32 v228, v42, v43
	v_cvt_pk_bf16_f32 v229, v44, v45
	ds_write_b128 v159, v[226:229]
	ds_read_b128 v[202:205], v160
	v_mov_b32_e32 v50, 0
	v_mov_b32_e32 v51, 0
	v_mov_b32_e32 v52, 0
	v_mov_b32_e32 v53, 0
	v_mov_b32_e32 v42, 0
	v_mov_b32_e32 v43, 0
	v_mov_b32_e32 v44, 0
	v_mov_b32_e32 v45, 0
	s_waitcnt lgkmcnt(6)
	global_store_dwordx4 v[216:217], v[190:193], off offset:256 nt
	v_cvt_pk_bf16_f32 v230, v38, v39
	v_cvt_pk_bf16_f32 v231, v40, v41
	v_cvt_pk_bf16_f32 v232, v30, v31
	v_cvt_pk_bf16_f32 v233, v32, v33
	ds_write_b128 v159, v[230:233]
	ds_read_b128 v[206:209], v160
	v_mov_b32_e32 v38, 0
	v_mov_b32_e32 v39, 0
	v_mov_b32_e32 v40, 0
	v_mov_b32_e32 v41, 0
	v_mov_b32_e32 v30, 0
	v_mov_b32_e32 v31, 0
	v_mov_b32_e32 v32, 0
	v_mov_b32_e32 v33, 0
	s_waitcnt lgkmcnt(6)
	global_store_dwordx4 v[218:219], v[194:197], off nt
	v_cvt_pk_bf16_f32 v226, v34, v35
	v_cvt_pk_bf16_f32 v227, v36, v37
	v_cvt_pk_bf16_f32 v228, v26, v27
	v_cvt_pk_bf16_f32 v229, v28, v29
	ds_write_b128 v159, v[226:229]
	ds_read_b128 v[162:165], v160
	v_mov_b32_e32 v34, 0
	v_mov_b32_e32 v35, 0
	v_mov_b32_e32 v36, 0
	v_mov_b32_e32 v37, 0
	v_mov_b32_e32 v26, 0
	v_mov_b32_e32 v27, 0
	v_mov_b32_e32 v28, 0
	v_mov_b32_e32 v29, 0
	s_waitcnt lgkmcnt(6)
	global_store_dwordx4 v[218:219], v[198:201], off offset:256 nt
	v_cvt_pk_bf16_f32 v230, v22, v23
	v_cvt_pk_bf16_f32 v231, v24, v25
	v_cvt_pk_bf16_f32 v232, v14, v15
	v_cvt_pk_bf16_f32 v233, v16, v17
	ds_write_b128 v159, v[230:233]
	ds_read_b128 v[166:169], v160
	v_mov_b32_e32 v22, 0
	v_mov_b32_e32 v23, 0
	v_mov_b32_e32 v24, 0
	v_mov_b32_e32 v25, 0
	v_mov_b32_e32 v14, 0
	v_mov_b32_e32 v15, 0
	v_mov_b32_e32 v16, 0
	v_mov_b32_e32 v17, 0
	s_waitcnt lgkmcnt(6)
	global_store_dwordx4 v[220:221], v[202:205], off nt
	v_cvt_pk_bf16_f32 v226, v18, v19
	v_cvt_pk_bf16_f32 v227, v20, v21
	v_cvt_pk_bf16_f32 v228, v10, v11
	v_cvt_pk_bf16_f32 v229, v12, v13
	ds_write_b128 v159, v[226:229]
	ds_read_b128 v[170:173], v160
	v_mov_b32_e32 v18, 0
	v_mov_b32_e32 v19, 0
	v_mov_b32_e32 v20, 0
	v_mov_b32_e32 v21, 0
	v_mov_b32_e32 v10, 0
	v_mov_b32_e32 v11, 0
	v_mov_b32_e32 v12, 0
	v_mov_b32_e32 v13, 0
	s_waitcnt lgkmcnt(6)
	global_store_dwordx4 v[220:221], v[206:209], off offset:256 nt
	v_cvt_pk_bf16_f32 v230, v6, v7
	v_cvt_pk_bf16_f32 v231, v8, v9
	v_cvt_pk_bf16_f32 v232, v2, v3
	v_cvt_pk_bf16_f32 v233, v4, v5
	ds_write_b128 v159, v[230:233]
	ds_read_b128 v[174:177], v160
	v_mov_b32_e32 v6, 0
	v_mov_b32_e32 v7, 0
	v_mov_b32_e32 v8, 0
	v_mov_b32_e32 v9, 0
	v_mov_b32_e32 v2, 0
	v_mov_b32_e32 v3, 0
	v_mov_b32_e32 v4, 0
	v_mov_b32_e32 v5, 0
	s_waitcnt lgkmcnt(6)
	global_store_dwordx4 v[222:223], v[162:165], off nt
	s_waitcnt lgkmcnt(4)
	global_store_dwordx4 v[222:223], v[166:169], off offset:256 nt
	s_waitcnt lgkmcnt(2)
	global_store_dwordx4 v[224:225], v[170:173], off nt
	s_waitcnt lgkmcnt(0)
	global_store_dwordx4 v[224:225], v[174:177], off offset:256 nt
	s_cbranch_vccnz .LBB0_244
	s_andn2_b64 vcc, exec, s[4:5]
	s_cbranch_vccnz .LBB0_243
	s_barrier
	s_branch .LBB0_243
